# k4 plus: FFN2 gate-up fp8 MFMAs use the unscaled f8f6f4 form (unit scales were loaded per MFMA before), one issue less per MFMA
# speedup vs baseline: 1.0335x; 1.0003x over previous
; #define PG8_STAGE(bufoff, gbase, voff) do { _Pragma("unroll") for (int _i = 0; _i < 2; ++_i) \
;         { unsigned _vo = (voff)[_i]; asm volatile("" : "+v"(_vo));     \
;         __builtin_amdgcn_global_load_lds((const unsigned*)((const char*)(gbase) + _vo), (PG8_LAS unsigned*)(lds + (bufoff) + ldsw + _i * 8192), 16, 0, 0); } } while (0)
; #define PG8_LDA(dst, b, h) do { _Pragma("unroll") for (int m = 0; m < 4; ++m) _Pragma("unroll") for (int k = 0; k < 2; ++k) dst[m][k] = *(const PG8_LAS bf16x8*)(lds + PG8_SA(b, h) + aoff + m * 2048 + k * 1024); } while (0)
; #define PG8_LDB(dst, b, h) do { _Pragma("unroll") for (int n = 0; n < 2; ++n) _Pragma("unroll") for (int k = 0; k < 2; ++k) dst[n][k] = *(const PG8_LAS bf16x8*)(lds + PG8_SB(b, h) + boff + n * 2048 + k * 1024); } while (0)
; #define PG8_WAIT_V(n) asm volatile("s_waitcnt vmcnt(" #n ")" ::: "memory")
; #define PG8_WAIT_L(n) asm volatile("s_waitcnt lgkmcnt(" #n ")" ::: "memory")
; #define PG8_BAR __builtin_amdgcn_s_barrier()
; #define PG8_SCHED __builtin_amdgcn_sched_barrier(0)
; template <class Epi, class Sched, bool ALIGN_EPI = false, bool SP2 = false, bool ABLK = false, bool F8 = false>
; __device__ __forceinline__ void gemm_phase(PG8_LAS unsigned char* lds, const Gemm g, const Sched& S, const Epi& E, const int wave_s) {
;     ...
;             const bool last = (t == nt - 2);
;             const char* a1 = cA + (size_t)(t + 1) * kstepA;
;             const char* a2 = last ? nA : cA + (size_t)(t + 2) * kstepA; const char* b2 = last ? nB : cB + (size_t)(t + 2) * kstep;
;             const char* a3 = a2 + kstepA; const char* b3 = b2 + kstep;
;             if (last && has_next) { S.a_ready(nxt); if constexpr (Epi::PREF) E.prefetch(nxt, wid, lane); }
;             if constexpr (SP2) {
;             PG8_LDB(B0, 0, 0); PG8_LDB(B1, 0, 1); PG8_SCHED; PG8_LDA(At, 0, 0); PG8_STAGE(PG8_SA(1, 1), a1 + hstepA, voffA);
;             PG8_WAIT_V(8); PG8_WAIT_L(0); PG8_BAR; PG8_MMA(0, 0, At, B0); PG8_MMA(0, 1, At, B1); PG8_BAR; PG8_SCHED;
;             PG8_LDA(At, 0, 1); PG8_STAGE(PG8_SB(0, 0), b2, voffB); PG8_STAGE(PG8_SB(0, 1), b2 + hstep, voffB); PG8_STAGE(PG8_SA(0, 0), a2, voffA);
;             PG8_WAIT_V(8); PG8_WAIT_L(0); PG8_BAR; PG8_MMA(1, 0, At, B0); PG8_MMA(1, 1, At, B1); PG8_BAR; PG8_SCHED;
.LBB0_810:
	v_add_u32_e32 v128, s61, v142
	ds_read_b128 v[148:151], v128
	ds_read_b128 v[152:155], v128 offset:1024
	ds_read_b128 v[156:159], v128 offset:2048
	ds_read_b128 v[160:163], v128 offset:3072
	v_add_u32_e32 v128, s62, v142
	ds_read_b128 v[164:167], v128
	ds_read_b128 v[168:171], v128 offset:1024
	ds_read_b128 v[172:175], v128 offset:2048
	ds_read_b128 v[176:179], v128 offset:3072
	s_add_u32 s58, s54, 0xfffc0080
	s_addc_u32 s59, s55, -1
	s_and_b64 s[56:57], s[56:57], exec
	s_cselect_b32 s57, s59, s43
	s_cselect_b32 s56, s58, s66
	s_cselect_b32 s59, s73, s41
	s_cselect_b32 s58, s72, s67
	ds_read_b128 v[180:183], v143
	ds_read_b128 v[184:187], v143 offset:1024
	ds_read_b128 v[188:191], v143 offset:2048
	ds_read_b128 v[192:195], v143 offset:3072
	ds_read_b128 v[196:199], v143 offset:4096
	ds_read_b128 v[200:203], v143 offset:5120
	ds_read_b128 v[204:207], v143 offset:6144
	ds_read_b128 v[208:211], v143 offset:7168
	s_add_i32 m0, s20, 0xc000
	s_nop 0
	global_load_lds_dwordx4 v147, s[54:55]
	s_add_i32 m0, s20, 0xe000
	s_nop 0
	global_load_lds_dwordx4 v140, s[54:55]
	s_waitcnt vmcnt(8)
	s_waitcnt lgkmcnt(0)
	s_barrier
	s_setprio 1
	s_waitcnt lgkmcnt(0)
	v_mfma_f32_16x16x128_f8f6f4 v[124:127], v[148:155], v[180:187], v[124:127]
	v_mfma_f32_16x16x128_f8f6f4 v[116:119], v[156:163], v[180:187], v[116:119]
	v_mfma_f32_16x16x128_f8f6f4 v[108:111], v[148:155], v[188:195], v[108:111]
	v_mfma_f32_16x16x128_f8f6f4 v[100:103], v[156:163], v[188:195], v[100:103]
	v_mfma_f32_16x16x128_f8f6f4 v[212:215], v[148:155], v[196:203], v[92:95]
	v_mfma_f32_16x16x128_f8f6f4 v[216:219], v[156:163], v[196:203], v[84:87]
	v_mfma_f32_16x16x128_f8f6f4 v[220:223], v[148:155], v[204:211], v[76:79]
	v_mfma_f32_16x16x128_f8f6f4 v[224:227], v[156:163], v[204:211], v[68:71]
	s_setprio 0
	s_setprio 1
	v_mfma_f32_16x16x128_f8f6f4 v[120:123], v[164:171], v[180:187], v[120:123]
	v_mfma_f32_16x16x128_f8f6f4 v[112:115], v[172:179], v[180:187], v[112:115]
	v_mfma_f32_16x16x128_f8f6f4 v[104:107], v[164:171], v[188:195], v[104:107]
	v_mfma_f32_16x16x128_f8f6f4 v[96:99], v[172:179], v[188:195], v[96:99]
	v_mfma_f32_16x16x128_f8f6f4 v[180:183], v[164:171], v[196:203], v[88:91]
	v_mfma_f32_16x16x128_f8f6f4 v[184:187], v[172:179], v[196:203], v[80:83]
	v_mfma_f32_16x16x128_f8f6f4 v[188:191], v[164:171], v[204:211], v[72:75]
	v_mfma_f32_16x16x128_f8f6f4 v[192:195], v[172:179], v[204:211], v[64:67]
	s_setprio 0
	s_barrier
	s_add_i32 s76, s61, s3
	s_nop 2
	ds_read_b128 v[64:67], v143 offset:16384
	ds_read_b128 v[68:71], v143 offset:17408
	ds_read_b128 v[72:75], v143 offset:18432
	ds_read_b128 v[76:79], v143 offset:19456
	ds_read_b128 v[80:83], v143 offset:20480
	ds_read_b128 v[84:87], v143 offset:21504
	ds_read_b128 v[88:91], v143 offset:22528
	ds_read_b128 v[92:95], v143 offset:23552
	s_mov_b32 m0, s76
	s_nop 0
	global_load_lds_dwordx4 v254, s[58:59]
	s_add_i32 m0, s76, 0x2000
	s_add_u32 s76, s58, 0x40000
	global_load_lds_dwordx4 v141, s[58:59]
	s_addc_u32 s77, s59, 0
	s_add_i32 s78, s62, s3
	s_mov_b32 m0, s78
	s_nop 0
	global_load_lds_dwordx4 v254, s[76:77]
	s_add_i32 m0, s78, 0x2000
	s_nop 0
	global_load_lds_dwordx4 v141, s[76:77]
	s_mov_b32 m0, s20
	s_nop 0
	global_load_lds_dwordx4 v147, s[56:57]
	s_mov_b32 m0, s21
	s_nop 0
	global_load_lds_dwordx4 v140, s[56:57]
	s_waitcnt vmcnt(8)
	s_waitcnt lgkmcnt(0)
	s_barrier
	s_setprio 1
	s_waitcnt lgkmcnt(0)
	v_mfma_f32_16x16x128_f8f6f4 v[60:63], v[148:155], v[64:71], v[60:63]
	v_mfma_f32_16x16x128_f8f6f4 v[52:55], v[156:163], v[64:71], v[52:55]
	v_mfma_f32_16x16x128_f8f6f4 v[44:47], v[148:155], v[72:79], v[44:47]
	v_mfma_f32_16x16x128_f8f6f4 v[204:207], v[156:163], v[72:79], v[36:39]
	v_mfma_f32_16x16x128_f8f6f4 v[208:211], v[148:155], v[80:87], v[28:31]
	v_mfma_f32_16x16x128_f8f6f4 v[230:233], v[156:163], v[80:87], v[20:23]
	v_mfma_f32_16x16x128_f8f6f4 v[234:237], v[148:155], v[88:95], v[12:15]
	v_mfma_f32_16x16x128_f8f6f4 v[238:241], v[156:163], v[88:95], v[4:7]
	s_setprio 0
	s_setprio 1
	v_mfma_f32_16x16x128_f8f6f4 v[56:59], v[164:171], v[64:71], v[56:59]
	v_mfma_f32_16x16x128_f8f6f4 v[48:51], v[172:179], v[64:71], v[48:51]
	v_mfma_f32_16x16x128_f8f6f4 v[40:43], v[164:171], v[72:79], v[40:43]
	v_mfma_f32_16x16x128_f8f6f4 v[242:245], v[172:179], v[72:79], v[32:35]
	v_mfma_f32_16x16x128_f8f6f4 v[246:249], v[164:171], v[80:87], v[24:27]
	v_mfma_f32_16x16x128_f8f6f4 v[250:253], v[172:179], v[80:87], v[16:19]
	v_mfma_f32_16x16x128_f8f6f4 v[132:135], v[164:171], v[88:95], v[8:11]
	v_mfma_f32_16x16x128_f8f6f4 v[136:139], v[172:179], v[88:95], v[0:3]
	s_setprio 0
	s_barrier
; #define PG8_STAGE(bufoff, gbase, voff) do { _Pragma("unroll") for (int _i = 0; _i < 2; ++_i) \
;         { unsigned _vo = (voff)[_i]; asm volatile("" : "+v"(_vo));     \
;         __builtin_amdgcn_global_load_lds((const unsigned*)((const char*)(gbase) + _vo), (PG8_LAS unsigned*)(lds + (bufoff) + ldsw + _i * 8192), 16, 0, 0); } } while (0)
; #define PG8_LDA(dst, b, h) do { _Pragma("unroll") for (int m = 0; m < 4; ++m) _Pragma("unroll") for (int k = 0; k < 2; ++k) dst[m][k] = *(const PG8_LAS bf16x8*)(lds + PG8_SA(b, h) + aoff + m * 2048 + k * 1024); } while (0)
; #define PG8_LDB(dst, b, h) do { _Pragma("unroll") for (int n = 0; n < 2; ++n) _Pragma("unroll") for (int k = 0; k < 2; ++k) dst[n][k] = *(const PG8_LAS bf16x8*)(lds + PG8_SB(b, h) + boff + n * 2048 + k * 1024); } while (0)
; #define PG8_WAIT_V(n) asm volatile("s_waitcnt vmcnt(" #n ")" ::: "memory")
; #define PG8_WAIT_L(n) asm volatile("s_waitcnt lgkmcnt(" #n ")" ::: "memory")
; #define PG8_BAR __builtin_amdgcn_s_barrier()
; #define PG8_SCHED __builtin_amdgcn_sched_barrier(0)
; template <class Epi, class Sched, bool ALIGN_EPI = false, bool SP2 = false, bool ABLK = false, bool F8 = false>
; __device__ __forceinline__ void gemm_phase(PG8_LAS unsigned char* lds, const Gemm g, const Sched& S, const Epi& E, const int wave_s) {
;     ...
;             PG8_LDB(B0, 1, 0); PG8_LDB(B1, 1, 1); PG8_SCHED; PG8_LDA(At, 1, 0); PG8_STAGE(PG8_SA(0, 1), a2 + hstepA, voffA);
;             PG8_WAIT_V(8); PG8_WAIT_L(0); PG8_BAR; PG8_MMA(0, 0, At, B0); PG8_MMA(0, 1, At, B1); PG8_BAR; PG8_SCHED;
;             PG8_LDA(At, 1, 1); PG8_STAGE(PG8_SB(1, 0), b3, voffB); PG8_STAGE(PG8_SB(1, 1), b3 + hstep, voffB); PG8_STAGE(PG8_SA(1, 0), a3, voffA);
;             PG8_WAIT_V(8); PG8_WAIT_L(0); PG8_BAR; PG8_MMA(1, 0, At, B0); PG8_MMA(1, 1, At, B1); PG8_BAR; PG8_SCHED;
	s_add_i32 s78, 0, 0x18000
	s_nop 2
	v_add_u32_e32 v8, s78, v142
	s_add_i32 s79, 0, 0x1c000
	ds_read_b128 v[0:3], v8
	ds_read_b128 v[4:7], v8 offset:1024
	ds_read_b128 v[148:151], v8 offset:2048
	ds_read_b128 v[152:155], v8 offset:3072
	v_add_u32_e32 v8, s79, v142
	ds_read_b128 v[156:159], v8
	ds_read_b128 v[160:163], v8 offset:1024
	ds_read_b128 v[164:167], v8 offset:2048
	ds_read_b128 v[168:171], v8 offset:3072
	s_add_u32 s76, s56, 0x40000
	s_mov_b32 m0, s22
	ds_read_b128 v[8:11], v143 offset:32768
	ds_read_b128 v[12:15], v143 offset:33792
	ds_read_b128 v[16:19], v143 offset:34816
	ds_read_b128 v[20:23], v143 offset:35840
	ds_read_b128 v[24:27], v143 offset:36864
	ds_read_b128 v[28:31], v143 offset:37888
	ds_read_b128 v[32:35], v143 offset:38912
	ds_read_b128 v[36:39], v143 offset:39936
	s_addc_u32 s77, s57, 0
	s_nop 0
	global_load_lds_dwordx4 v147, s[76:77]
	s_mov_b32 m0, s23
	s_nop 0
	global_load_lds_dwordx4 v140, s[76:77]
	s_waitcnt vmcnt(8)
	s_waitcnt lgkmcnt(0)
	s_barrier
	s_setprio 1
	s_waitcnt lgkmcnt(0)
	v_mfma_f32_16x16x128_f8f6f4 v[124:127], v[0:7], v[8:15], v[124:127]
	v_mfma_f32_16x16x128_f8f6f4 v[116:119], v[148:155], v[8:15], v[116:119]
	v_mfma_f32_16x16x128_f8f6f4 v[108:111], v[0:7], v[16:23], v[108:111]
	v_mfma_f32_16x16x128_f8f6f4 v[100:103], v[148:155], v[16:23], v[100:103]
	v_mfma_f32_16x16x128_f8f6f4 v[92:95], v[0:7], v[24:31], v[212:215]
	v_mfma_f32_16x16x128_f8f6f4 v[84:87], v[148:155], v[24:31], v[216:219]
	v_mfma_f32_16x16x128_f8f6f4 v[76:79], v[0:7], v[32:39], v[220:223]
	v_mfma_f32_16x16x128_f8f6f4 v[68:71], v[148:155], v[32:39], v[224:227]
	s_setprio 0
	s_setprio 1
	v_mfma_f32_16x16x128_f8f6f4 v[120:123], v[156:163], v[8:15], v[120:123]
	v_mfma_f32_16x16x128_f8f6f4 v[112:115], v[164:171], v[8:15], v[112:115]
	v_mfma_f32_16x16x128_f8f6f4 v[104:107], v[156:163], v[16:23], v[104:107]
	v_mfma_f32_16x16x128_f8f6f4 v[96:99], v[164:171], v[16:23], v[96:99]
	v_mfma_f32_16x16x128_f8f6f4 v[88:91], v[156:163], v[24:31], v[180:183]
	v_mfma_f32_16x16x128_f8f6f4 v[80:83], v[164:171], v[24:31], v[184:187]
	v_mfma_f32_16x16x128_f8f6f4 v[72:75], v[156:163], v[32:39], v[188:191]
	v_mfma_f32_16x16x128_f8f6f4 v[64:67], v[164:171], v[32:39], v[192:195]
	s_setprio 0
	s_barrier
	ds_read_b128 v[172:175], v143 offset:49152
	ds_read_b128 v[176:179], v143 offset:50176
	ds_read_b128 v[180:183], v143 offset:51200
	ds_read_b128 v[184:187], v143 offset:52224
	ds_read_b128 v[188:191], v143 offset:53248
	ds_read_b128 v[192:195], v143 offset:54272
	ds_read_b128 v[196:199], v143 offset:55296
	ds_read_b128 v[200:203], v143 offset:56320
	s_add_i32 s76, s78, s3
	s_add_u32 vcc_lo, s58, s12
	s_addc_u32 vcc_hi, s59, s13
	s_mov_b32 m0, s76
	s_nop 0
	global_load_lds_dwordx4 v254, vcc
	s_add_i32 m0, s76, 0x2000
	s_add_u32 vcc_lo, s58, s12
	s_addc_u32 vcc_hi, s59, s13
	s_add_u32 s58, s58, 0x40080
	global_load_lds_dwordx4 v141, vcc
	s_addc_u32 s59, s59, 0
	s_add_i32 s76, s79, s3
	s_mov_b32 m0, s76
	s_nop 0
	global_load_lds_dwordx4 v254, s[58:59]
	s_add_i32 m0, s76, 0x2000
	s_nop 0
	global_load_lds_dwordx4 v141, s[58:59]
	s_mov_b32 m0, s33
	s_add_u32 vcc_lo, s56, s12
	s_addc_u32 vcc_hi, s57, s13
	v_mov_b32_e32 v128, v140
	global_load_lds_dwordx4 v147, vcc
	s_mov_b32 m0, s51
	s_add_u32 vcc_lo, s56, s12
	s_addc_u32 vcc_hi, s57, s13
	global_load_lds_dwordx4 v140, vcc
	s_waitcnt vmcnt(8)
	s_waitcnt lgkmcnt(0)
	s_barrier
	s_setprio 1
	s_waitcnt lgkmcnt(0)
	v_mfma_f32_16x16x128_f8f6f4 v[60:63], v[0:7], v[172:179], v[60:63]
	v_mfma_f32_16x16x128_f8f6f4 v[52:55], v[148:155], v[172:179], v[52:55]
	v_mfma_f32_16x16x128_f8f6f4 v[44:47], v[0:7], v[180:187], v[44:47]
	v_mfma_f32_16x16x128_f8f6f4 v[36:39], v[148:155], v[180:187], v[204:207]
	v_mfma_f32_16x16x128_f8f6f4 v[28:31], v[0:7], v[188:195], v[208:211]
	v_mfma_f32_16x16x128_f8f6f4 v[20:23], v[148:155], v[188:195], v[230:233]
	v_mfma_f32_16x16x128_f8f6f4 v[12:15], v[0:7], v[196:203], v[234:237]
	v_mfma_f32_16x16x128_f8f6f4 v[4:7], v[148:155], v[196:203], v[238:241]
	s_setprio 0
	s_setprio 1
	v_mfma_f32_16x16x128_f8f6f4 v[56:59], v[156:163], v[172:179], v[56:59]
	v_mfma_f32_16x16x128_f8f6f4 v[48:51], v[164:171], v[172:179], v[48:51]
	v_mfma_f32_16x16x128_f8f6f4 v[40:43], v[156:163], v[180:187], v[40:43]
	v_mfma_f32_16x16x128_f8f6f4 v[32:35], v[164:171], v[180:187], v[242:245]
	v_mfma_f32_16x16x128_f8f6f4 v[24:27], v[156:163], v[188:195], v[246:249]
	v_mfma_f32_16x16x128_f8f6f4 v[16:19], v[164:171], v[188:195], v[250:253]
	v_mfma_f32_16x16x128_f8f6f4 v[8:11], v[156:163], v[196:203], v[132:135]
	v_mfma_f32_16x16x128_f8f6f4 v[0:3], v[164:171], v[196:203], v[136:139]
	s_setprio 0
	s_barrier
	s_add_i32 s74, s74, 2
	s_add_u32 s54, s54, 0x100
	s_addc_u32 s55, s55, 0
	s_add_u32 s72, s72, 0x100
	s_addc_u32 s73, s73, 0
	s_cmp_gt_u32 s74, 13
	s_cbranch_scc1 .LBB0_813
